# baseline (speedup 1.0000x reference)
; __device__ __forceinline__ void xcd_barrier(const XcdBarrier& b, unsigned epoch) {
;     asm volatile("s_waitcnt vmcnt(0)" ::: "memory");
;     __syncthreads();
; __global__ void __launch_bounds__(512, 2) mega(Params p) {
;     ...
;         phase_E(p, l);
;         if (l == 0) xcd_barrier(xb, e0 + 4u);
.LBB0_542:
	s_andn2_b64 vcc, exec, s[0:1]
	s_mov_b64 s[0:1], -1
	s_cbranch_vccnz .LBB0_79
	s_waitcnt vmcnt(0)
	v_mov_b32_e32 v0, v208
	s_barrier
	s_nop 0
	v_cmp_eq_u32_e32 vcc, 0, v0
	s_and_saveexec_b64 s[0:1], vcc
	s_cbranch_execz .LBB0_78
	v_readlane_b32 s4, v234, 46
	s_lshl_b32 s4, s4, 8
	s_and_b32 s5, s50, 63
	s_add_i32 s4, s4, s5
	s_add_i32 s4, s4, 128
	s_lshl_b32 s4, s4, 6
	s_add_i32 s4, s4, 0x4000
	s_add_u32 s4, s92, s4
	s_addc_u32 s5, s93, 0
	v_mov_b32_e32 v0, 0
	s_waitcnt vmcnt(0) lgkmcnt(0)
	s_and_b32 s6, s51, 7
	s_mul_i32 s6, s6, 3
	s_add_i32 s6, s6, 8
	s_lshl_b32 s6, 1, s6
	s_add_i32 s6, s6, 1
	v_mov_b32_e32 v2, s6
	global_atomic_add v0, v2, s[4:5]
	s_waitcnt vmcnt(0)
.Lgbc_spin:
	global_load_dword v1, v0, s[4:5] sc1
	s_waitcnt vmcnt(0)
	v_and_b32_e32 v3, 0xff, v1
	v_cmp_gt_u32_e32 vcc, 4, v3
	s_cbranch_vccz .Lgbc_done
	s_sleep 1
	s_branch .Lgbc_spin
.Lgbc_done:
	v_lshrrev_b32_e32 v3, 8, v1
	v_add_u32_e32 v2, -1, v3
	v_and_b32_e32 v2, v2, v3
	v_cmp_ne_u32_e32 vcc, 0, v2
	s_cbranch_vccz .Lgbc_fast
	buffer_wbl2 sc1
	s_waitcnt vmcnt(0)
	s_add_u32 s4, s4, 0x1000
	s_addc_u32 s5, s5, 0
	global_atomic_add v0, v210, s[4:5]
	s_waitcnt vmcnt(0)
